# P4 epilogue fast path: rstd = v_rsq_f32(rss/1024 + eps) without the denormal-range rescue sequence (argument >= 1e-6, bit-identical)
# baseline (speedup 1.0000x reference)
;     __device__ __forceinline__ void operator()(f32x4 (&acc)[2][2][4][2], const Unit& u, int wr, int wc, int fr, int fq) const {
;     ...
;         const int tok0 = 254 * u.pm - 1;
;         const int pcol = wc * 32 + 8 * fq;
;         const bool bnd = (tok0 < 0) || (((tok0 & (SEQP - 1)) + 256) >= SEQP) || (tok0 + 256 > MTOK);
; #pragma unroll
;         for (int ai = 0; ai < 2; ++ai)
; #pragma unroll
;             for (int m = 0; m < 4; ++m) {
;                 const int tok = tok0 + ai * 128 + wr * 64 + m * 16 + fr;
;                 if (bnd) {
;                     const bool valid = (tok >= 0) && (tok < MTOK);
;                     float rs = 0.f; if (valid) rs = rsqrtf(rss[tok] * (1.0f / 1024.0f) + EPSV);
; #pragma unroll
;                     for (int bj = 0; bj < 2; ++bj)
; #pragma unroll
;                         for (int n = 0; n < 2; ++n) { f32x4 x = acc[ai][bj][m][n] * rs;
; #pragma unroll
;                             for (int j = 0; j < 4; ++j) x[j] = valid ? x[j] : 0.f;
;                             acc[ai][bj][m][n] = x; }
;                 } else {
;                     const float rs = rsqrtf(rss[tok] * (1.0f / 1024.0f) + EPSV);
; #pragma unroll
;                     for (int bj = 0; bj < 2; ++bj)
; #pragma unroll
;                         for (int n = 0; n < 2; ++n) acc[ai][bj][m][n] = acc[ai][bj][m][n] * rs;
.LBB0_568:
	s_mul_i32 s36, s12, 0xfe
	s_add_i32 s4, s36, -1
	s_and_b32 s0, s4, 0xf00
	s_cmpk_lg_i32 s0, 0xf00
	s_cselect_b64 s[0:1], -1, 0
	s_add_i32 s5, s12, 0xfffffdfc
	s_cmp_gt_u32 s5, 0xfffffdfc
	v_mov_b32_e32 v190, v237
	v_mov_b32_e32 v228, v236
	s_cselect_b64 s[6:7], -1, 0
	s_and_b64 s[12:13], s[6:7], s[0:1]
	v_add_u32_e32 v245, s48, v228
	v_add_u32_e32 v152, s4, v245
	s_mov_b64 s[0:1], -1
	s_and_b64 vcc, exec, s[12:13]
	s_mov_b32 s93, s17
	s_cbranch_vccz .LBB0_570
	v_ashrrev_i32_e32 v1, 31, v152
	v_mov_b32_e32 v0, v152
	v_lshl_add_u64 v[0:1], v[0:1], 2, s[60:61]
	s_waitcnt vmcnt(0)
	v_fmamk_f32 v0, v248, 0x3a800000, v242
	s_mov_b64 s[0:1], 0
	v_rsq_f32_e32 v4, v0
	s_nop 0
	v_pk_mul_f32 v[34:35], v[142:143], v[4:5] op_sel_hi:[1,0]
	v_pk_mul_f32 v[32:33], v[140:141], v[4:5] op_sel_hi:[1,0]
	v_pk_mul_f32 v[2:3], v[138:139], v[4:5] op_sel_hi:[1,0]
	v_pk_mul_f32 v[0:1], v[136:137], v[4:5] op_sel_hi:[1,0]
	v_pk_mul_f32 v[38:39], v[134:135], v[4:5] op_sel_hi:[1,0]
	v_pk_mul_f32 v[36:37], v[132:133], v[4:5] op_sel_hi:[1,0]
	v_pk_mul_f32 v[6:7], v[130:131], v[4:5] op_sel_hi:[1,0]
	v_pk_mul_f32 v[4:5], v[128:129], v[4:5] op_sel_hi:[1,0]

;     __device__ __forceinline__ void operator()(f32x4 (&acc)[2][2][4][2], const Unit& u, int wr, int wc, int fr, int fq) const {
;     ...
;                     const float rs = rsqrtf(rss[tok] * (1.0f / 1024.0f) + EPSV);
; #pragma unroll
;                     for (int bj = 0; bj < 2; ++bj)
; #pragma unroll
;                         for (int n = 0; n < 2; ++n) acc[ai][bj][m][n] = acc[ai][bj][m][n] * rs;
.LBB0_574:
	v_cndmask_b32_e64 v129, 0, 1, s[12:13]
	v_add_u32_e32 v128, 16, v152
	v_cmp_ne_u32_e64 s[6:7], 1, v129
	s_andn2_b64 vcc, exec, s[12:13]
	s_mov_b64 s[0:1], -1
	s_cbranch_vccnz .LBB0_588
	v_ashrrev_i32_e32 v129, 31, v128
	v_lshl_add_u64 v[130:131], v[128:129], 2, s[60:61]
	s_waitcnt vmcnt(0)
	v_fmamk_f32 v129, v249, 0x3a800000, v242
	v_rsq_f32_e32 v130, v129
	s_nop 0
	v_pk_mul_f32 v[192:193], v[126:127], v[130:131] op_sel_hi:[1,0]
	v_pk_mul_f32 v[194:195], v[124:125], v[130:131] op_sel_hi:[1,0]
	v_pk_mul_f32 v[158:159], v[122:123], v[130:131] op_sel_hi:[1,0]
	v_pk_mul_f32 v[160:161], v[120:121], v[130:131] op_sel_hi:[1,0]
	v_pk_mul_f32 v[196:197], v[118:119], v[130:131] op_sel_hi:[1,0]
	v_pk_mul_f32 v[198:199], v[116:117], v[130:131] op_sel_hi:[1,0]
	v_pk_mul_f32 v[162:163], v[114:115], v[130:131] op_sel_hi:[1,0]
	v_pk_mul_f32 v[164:165], v[112:113], v[130:131] op_sel_hi:[1,0]
	s_cbranch_execz .LBB0_589

;     __device__ __forceinline__ void operator()(f32x4 (&acc)[2][2][4][2], const Unit& u, int wr, int wc, int fr, int fq) const {
;     ...
;                     const float rs = rsqrtf(rss[tok] * (1.0f / 1024.0f) + EPSV);
; #pragma unroll
;                     for (int bj = 0; bj < 2; ++bj)
; #pragma unroll
;                         for (int n = 0; n < 2; ++n) acc[ai][bj][m][n] = acc[ai][bj][m][n] * rs;
.LBB0_577:
	v_ashrrev_i32_e32 v113, 31, v112
	v_lshl_add_u64 v[114:115], v[112:113], 2, s[60:61]
	s_waitcnt vmcnt(0)
	v_fmamk_f32 v113, v250, 0x3a800000, v242
	v_rsq_f32_e32 v114, v113
	s_nop 0
	v_pk_mul_f32 v[200:201], v[54:55], v[114:115] op_sel_hi:[1,0]
	v_pk_mul_f32 v[202:203], v[52:53], v[114:115] op_sel_hi:[1,0]
	v_pk_mul_f32 v[166:167], v[50:51], v[114:115] op_sel_hi:[1,0]
	v_pk_mul_f32 v[168:169], v[48:49], v[114:115] op_sel_hi:[1,0]
	v_pk_mul_f32 v[204:205], v[22:23], v[114:115] op_sel_hi:[1,0]
	v_pk_mul_f32 v[206:207], v[20:21], v[114:115] op_sel_hi:[1,0]
	v_pk_mul_f32 v[170:171], v[18:19], v[114:115] op_sel_hi:[1,0]
	v_pk_mul_f32 v[172:173], v[16:17], v[114:115] op_sel_hi:[1,0]
	s_cbranch_execz .LBB0_593

;     __device__ __forceinline__ void operator()(f32x4 (&acc)[2][2][4][2], const Unit& u, int wr, int wc, int fr, int fq) const {
;     ...
;                     const float rs = rsqrtf(rss[tok] * (1.0f / 1024.0f) + EPSV);
; #pragma unroll
;                     for (int bj = 0; bj < 2; ++bj)
; #pragma unroll
;                         for (int n = 0; n < 2; ++n) acc[ai][bj][m][n] = acc[ai][bj][m][n] * rs;
.LBB0_579:
	v_ashrrev_i32_e32 v113, 31, v112
	v_lshl_add_u64 v[16:17], v[112:113], 2, s[60:61]
	s_waitcnt vmcnt(0)
	v_fmamk_f32 v16, v251, 0x3a800000, v242
	v_rsq_f32_e32 v20, v16
	s_nop 0
	v_pk_mul_f32 v[50:51], v[46:47], v[20:21] op_sel_hi:[1,0]
	v_pk_mul_f32 v[48:49], v[44:45], v[20:21] op_sel_hi:[1,0]
	v_pk_mul_f32 v[18:19], v[42:43], v[20:21] op_sel_hi:[1,0]
	v_pk_mul_f32 v[16:17], v[40:41], v[20:21] op_sel_hi:[1,0]
	v_pk_mul_f32 v[54:55], v[14:15], v[20:21] op_sel_hi:[1,0]
	v_pk_mul_f32 v[52:53], v[12:13], v[20:21] op_sel_hi:[1,0]
	v_pk_mul_f32 v[22:23], v[10:11], v[20:21] op_sel_hi:[1,0]
	v_pk_mul_f32 v[20:21], v[8:9], v[20:21] op_sel_hi:[1,0]
	s_cbranch_execz .LBB0_597

;     __device__ __forceinline__ void operator()(f32x4 (&acc)[2][2][4][2], const Unit& u, int wr, int wc, int fr, int fq) const {
;     ...
;                     const float rs = rsqrtf(rss[tok] * (1.0f / 1024.0f) + EPSV);
; #pragma unroll
;                     for (int bj = 0; bj < 2; ++bj)
; #pragma unroll
;                         for (int n = 0; n < 2; ++n) acc[ai][bj][m][n] = acc[ai][bj][m][n] * rs;
.LBB0_581:
	v_ashrrev_i32_e32 v113, 31, v112
	v_lshl_add_u64 v[8:9], v[112:113], 2, s[60:61]
	s_waitcnt vmcnt(0)
	v_fmamk_f32 v8, v252, 0x3a800000, v242
	v_rsq_f32_e32 v12, v8
	s_nop 0
	v_pk_mul_f32 v[42:43], v[110:111], v[12:13] op_sel_hi:[1,0]
	v_pk_mul_f32 v[40:41], v[108:109], v[12:13] op_sel_hi:[1,0]
	v_pk_mul_f32 v[10:11], v[106:107], v[12:13] op_sel_hi:[1,0]
	v_pk_mul_f32 v[8:9], v[104:105], v[12:13] op_sel_hi:[1,0]
	v_pk_mul_f32 v[46:47], v[102:103], v[12:13] op_sel_hi:[1,0]
	v_pk_mul_f32 v[44:45], v[100:101], v[12:13] op_sel_hi:[1,0]
	v_pk_mul_f32 v[14:15], v[98:99], v[12:13] op_sel_hi:[1,0]
	v_pk_mul_f32 v[12:13], v[96:97], v[12:13] op_sel_hi:[1,0]
	s_cbranch_execz .LBB0_601

;     __device__ __forceinline__ void operator()(f32x4 (&acc)[2][2][4][2], const Unit& u, int wr, int wc, int fr, int fq) const {
;     ...
;                     const float rs = rsqrtf(rss[tok] * (1.0f / 1024.0f) + EPSV);
; #pragma unroll
;                     for (int bj = 0; bj < 2; ++bj)
; #pragma unroll
;                         for (int n = 0; n < 2; ++n) acc[ai][bj][m][n] = acc[ai][bj][m][n] * rs;
.LBB0_583:
	v_ashrrev_i32_e32 v97, 31, v96
	v_lshl_add_u64 v[98:99], v[96:97], 2, s[60:61]
	s_waitcnt vmcnt(0)
	v_fmamk_f32 v97, v253, 0x3a800000, v242
	v_rsq_f32_e32 v98, v97
	s_nop 0
	v_pk_mul_f32 v[208:209], v[94:95], v[98:99] op_sel_hi:[1,0]
	v_pk_mul_f32 v[210:211], v[92:93], v[98:99] op_sel_hi:[1,0]
	v_pk_mul_f32 v[174:175], v[90:91], v[98:99] op_sel_hi:[1,0]
	v_pk_mul_f32 v[176:177], v[88:89], v[98:99] op_sel_hi:[1,0]
	v_pk_mul_f32 v[212:213], v[86:87], v[98:99] op_sel_hi:[1,0]
	v_pk_mul_f32 v[214:215], v[84:85], v[98:99] op_sel_hi:[1,0]
	v_pk_mul_f32 v[178:179], v[82:83], v[98:99] op_sel_hi:[1,0]
	v_pk_mul_f32 v[180:181], v[80:81], v[98:99] op_sel_hi:[1,0]
	s_cbranch_execz .LBB0_605

;     __device__ __forceinline__ void operator()(f32x4 (&acc)[2][2][4][2], const Unit& u, int wr, int wc, int fr, int fq) const {
;     ...
;                     const float rs = rsqrtf(rss[tok] * (1.0f / 1024.0f) + EPSV);
; #pragma unroll
;                     for (int bj = 0; bj < 2; ++bj)
; #pragma unroll
;                         for (int n = 0; n < 2; ++n) acc[ai][bj][m][n] = acc[ai][bj][m][n] * rs;
.LBB0_585:
	v_ashrrev_i32_e32 v81, 31, v80
	v_lshl_add_u64 v[82:83], v[80:81], 2, s[60:61]
	s_waitcnt vmcnt(0)
	v_fmamk_f32 v81, v229, 0x3a800000, v242
	v_rsq_f32_e32 v82, v81
	s_nop 0
	v_pk_mul_f32 v[216:217], v[62:63], v[82:83] op_sel_hi:[1,0]
	v_pk_mul_f32 v[218:219], v[60:61], v[82:83] op_sel_hi:[1,0]
	v_pk_mul_f32 v[182:183], v[58:59], v[82:83] op_sel_hi:[1,0]
	v_pk_mul_f32 v[184:185], v[56:57], v[82:83] op_sel_hi:[1,0]
	v_pk_mul_f32 v[220:221], v[30:31], v[82:83] op_sel_hi:[1,0]
	v_pk_mul_f32 v[222:223], v[28:29], v[82:83] op_sel_hi:[1,0]
	v_pk_mul_f32 v[186:187], v[26:27], v[82:83] op_sel_hi:[1,0]
	v_pk_mul_f32 v[188:189], v[24:25], v[82:83] op_sel_hi:[1,0]
	s_cbranch_execz .LBB0_609

;     __device__ __forceinline__ void operator()(f32x4 (&acc)[2][2][4][2], const Unit& u, int wr, int wc, int fr, int fq) const {
;     ...
;                     const float rs = rsqrtf(rss[tok] * (1.0f / 1024.0f) + EPSV);
; #pragma unroll
;                     for (int bj = 0; bj < 2; ++bj)
; #pragma unroll
;                         for (int n = 0; n < 2; ++n) acc[ai][bj][m][n] = acc[ai][bj][m][n] * rs;
.LBB0_587:
	v_ashrrev_i32_e32 v81, 31, v80
	v_lshl_add_u64 v[24:25], v[80:81], 2, s[60:61]
	s_waitcnt vmcnt(0)
	v_fmamk_f32 v24, v230, 0x3a800000, v242
	v_rsq_f32_e32 v28, v24
	s_nop 0
	v_pk_mul_f32 v[58:59], v[78:79], v[28:29] op_sel_hi:[1,0]
	v_pk_mul_f32 v[56:57], v[76:77], v[28:29] op_sel_hi:[1,0]
	v_pk_mul_f32 v[26:27], v[74:75], v[28:29] op_sel_hi:[1,0]
	v_pk_mul_f32 v[24:25], v[72:73], v[28:29] op_sel_hi:[1,0]
	v_pk_mul_f32 v[62:63], v[70:71], v[28:29] op_sel_hi:[1,0]
	v_pk_mul_f32 v[60:61], v[68:69], v[28:29] op_sel_hi:[1,0]
	v_pk_mul_f32 v[30:31], v[66:67], v[28:29] op_sel_hi:[1,0]
	v_pk_mul_f32 v[28:29], v[64:65], v[28:29] op_sel_hi:[1,0]
	s_cbranch_execnz .LBB0_616
	s_branch .LBB0_613
